# attention P.V stage: V fragment LDS reads issued two groups ahead with counted lgkmcnt waits instead of one wait per MFMA
# speedup vs baseline: 1.0102x; 1.0102x over previous
; __device__ __forceinline__ void attn_phase(unsigned char* smem, const Params& P, int layer) {
;     ...
;             mx = fmaxf(mx, __shfl_xor(mx, 16)); mx = fmaxf(mx, __shfl_xor(mx, 32));
;             float l = 0.f;
; #pragma unroll
;             for (int tt = 0; tt < 10; ++tt)
; #pragma unroll
;                 for (int j = 0; j < 4; ++j) { const float pv = __expf(sc[tt][j] - mx); sc[tt][j] = pv; l += pv; }
;             l += __shfl_xor(l, 16); l += __shfl_xor(l, 32); l += __expf(sink - mx);
;             const float linv = 1.0f / l;
.LBB0_502:
	s_or_b64 exec, exec, vcc
	v_max_f32_e32 v16, v82, v82
	s_waitcnt vmcnt(0)
	v_max_f32_e32 v17, v33, v33
	v_max_f32_e32 v16, v17, v16
	v_max3_f32 v16, v16, v75, v81
	v_max3_f32 v16, v16, v76, v80
	v_max3_f32 v16, v16, v72, v74
	v_max3_f32 v16, v16, v73, v78
	v_max3_f32 v16, v16, v77, v83
	v_max3_f32 v16, v16, v79, v85
	v_max3_f32 v16, v16, v84, v88
	v_max3_f32 v16, v16, v86, v90
	v_max3_f32 v16, v16, v89, v92
	v_max3_f32 v16, v16, v91, v94
	v_max3_f32 v16, v16, v93, v96
	v_max3_f32 v16, v16, v95, v98
	v_max3_f32 v16, v16, v97, v100
	v_max3_f32 v16, v16, v99, v102
	v_max3_f32 v16, v16, v101, v104
	v_max3_f32 v16, v16, v103, v21
	v_max3_f32 v16, v16, v20, v106
	s_mov_b32 s4, 0xff800000
	v_max3_f32 v16, v16, v105, s4
	ds_bpermute_b32 v17, v43, v16
	s_addk_i32 s76, 0x200
	s_add_u32 s96, s96, 4
	s_addc_u32 s97, s97, 0
	v_lshl_add_u64 v[36:37], v[36:37], 0, s[46:47]
	s_waitcnt lgkmcnt(0)
	v_max_f32_e32 v17, v17, v17
	v_max_f32_e32 v16, v16, v17
	ds_bpermute_b32 v17, v44, v16
	s_cmpk_eq_i32 s76, 0x800
	s_waitcnt lgkmcnt(0)
	v_max_f32_e32 v17, v17, v17
	v_max_f32_e32 v87, v16, v17
	v_sub_f32_e32 v17, v75, v87
	v_mul_f32_e32 v17, 0x3fb8aa3b, v17
	v_exp_f32_e32 v75, v17
	v_sub_f32_e32 v17, v81, v87
	v_mul_f32_e32 v17, 0x3fb8aa3b, v17
	v_exp_f32_e32 v81, v17
	v_sub_f32_e32 v17, v76, v87
	v_mul_f32_e32 v17, 0x3fb8aa3b, v17
	v_exp_f32_e32 v107, v17
	v_sub_f32_e32 v17, v80, v87
	v_mul_f32_e32 v17, 0x3fb8aa3b, v17
	v_exp_f32_e32 v108, v17
	v_sub_f32_e32 v17, v72, v87
	v_mul_f32_e32 v17, 0x3fb8aa3b, v17
	v_exp_f32_e32 v109, v17
	v_sub_f32_e32 v17, v74, v87
	v_mul_f32_e32 v17, 0x3fb8aa3b, v17
	v_exp_f32_e32 v110, v17
	v_sub_f32_e32 v17, v73, v87
	v_mul_f32_e32 v17, 0x3fb8aa3b, v17
	v_exp_f32_e32 v111, v17
	v_sub_f32_e32 v17, v78, v87
	v_mul_f32_e32 v17, 0x3fb8aa3b, v17
	v_exp_f32_e32 v80, v17
	v_sub_f32_e32 v17, v77, v87
	v_mul_f32_e32 v17, 0x3fb8aa3b, v17
	v_exp_f32_e32 v112, v17
	v_sub_f32_e32 v17, v83, v87
	v_mul_f32_e32 v17, 0x3fb8aa3b, v17
	v_exp_f32_e32 v113, v17
	v_sub_f32_e32 v17, v79, v87
	v_mul_f32_e32 v17, 0x3fb8aa3b, v17
	v_exp_f32_e32 v114, v17
	v_sub_f32_e32 v17, v85, v87
	v_mul_f32_e32 v17, 0x3fb8aa3b, v17
	v_exp_f32_e32 v115, v17
	v_sub_f32_e32 v17, v84, v87
	v_mul_f32_e32 v17, 0x3fb8aa3b, v17
	v_exp_f32_e32 v116, v17
	v_sub_f32_e32 v17, v88, v87
	v_mul_f32_e32 v17, 0x3fb8aa3b, v17
	v_exp_f32_e32 v117, v17
	v_sub_f32_e32 v17, v86, v87
	v_sub_f32_e32 v16, v82, v87
	v_mul_f32_e32 v17, 0x3fb8aa3b, v17
	v_mul_f32_e32 v16, 0x3fb8aa3b, v16
	v_exp_f32_e32 v118, v17
	v_sub_f32_e32 v17, v90, v87
	v_exp_f32_e32 v26, v16
	v_mul_f32_e32 v17, 0x3fb8aa3b, v17
	v_exp_f32_e32 v27, v17
	v_sub_f32_e32 v17, v89, v87
	v_mul_f32_e32 v17, 0x3fb8aa3b, v17
	v_exp_f32_e32 v73, v17
	v_sub_f32_e32 v17, v92, v87
	v_add_f32_e32 v16, 0, v26
	v_mul_f32_e32 v17, 0x3fb8aa3b, v17
	v_add_f32_e32 v16, v75, v16
	v_exp_f32_e32 v76, v17
	v_sub_f32_e32 v17, v91, v87
	v_add_f32_e32 v16, v81, v16
	v_mul_f32_e32 v17, 0x3fb8aa3b, v17
	v_add_f32_e32 v16, v107, v16
	v_exp_f32_e32 v78, v17
	v_sub_f32_e32 v17, v94, v87
	v_add_f32_e32 v16, v108, v16
	v_mul_f32_e32 v17, 0x3fb8aa3b, v17
	v_add_f32_e32 v16, v109, v16
	v_exp_f32_e32 v119, v17
	v_sub_f32_e32 v17, v93, v87
	v_add_f32_e32 v16, v110, v16
	v_mul_f32_e32 v17, 0x3fb8aa3b, v17
	v_add_f32_e32 v16, v111, v16
	v_exp_f32_e32 v120, v17
	v_sub_f32_e32 v17, v96, v87
	v_add_f32_e32 v16, v80, v16
	v_mul_f32_e32 v17, 0x3fb8aa3b, v17
	v_add_f32_e32 v16, v112, v16
	v_exp_f32_e32 v121, v17
	v_sub_f32_e32 v17, v95, v87
	v_add_f32_e32 v16, v113, v16
	v_mul_f32_e32 v17, 0x3fb8aa3b, v17
	v_add_f32_e32 v16, v114, v16
	v_exp_f32_e32 v122, v17
	v_sub_f32_e32 v17, v98, v87
	v_add_f32_e32 v16, v115, v16
	v_mul_f32_e32 v17, 0x3fb8aa3b, v17
	v_add_f32_e32 v16, v116, v16
	v_exp_f32_e32 v22, v17
	v_sub_f32_e32 v17, v97, v87
	v_add_f32_e32 v16, v117, v16
	v_mul_f32_e32 v17, 0x3fb8aa3b, v17
	v_add_f32_e32 v16, v118, v16
	v_exp_f32_e32 v23, v17
	v_sub_f32_e32 v17, v100, v87
	v_add_f32_e32 v16, v27, v16
	v_mul_f32_e32 v17, 0x3fb8aa3b, v17
	v_add_f32_e32 v16, v73, v16
	v_exp_f32_e32 v24, v17
	v_sub_f32_e32 v17, v99, v87
	v_add_f32_e32 v16, v76, v16
	v_mul_f32_e32 v17, 0x3fb8aa3b, v17
	v_add_f32_e32 v16, v78, v16
	v_exp_f32_e32 v25, v17
	v_sub_f32_e32 v17, v102, v87
	v_add_f32_e32 v16, v119, v16
	v_mul_f32_e32 v17, 0x3fb8aa3b, v17
	v_add_f32_e32 v16, v120, v16
	v_exp_f32_e32 v72, v17
	v_sub_f32_e32 v17, v101, v87
	v_add_f32_e32 v16, v121, v16
	v_mul_f32_e32 v17, 0x3fb8aa3b, v17
	v_add_f32_e32 v16, v122, v16
	v_exp_f32_e32 v74, v17
	v_sub_f32_e32 v17, v104, v87
	v_add_f32_e32 v16, v22, v16
	v_mul_f32_e32 v17, 0x3fb8aa3b, v17
	v_add_f32_e32 v16, v23, v16
	v_exp_f32_e32 v77, v17
	v_sub_f32_e32 v17, v103, v87
	v_add_f32_e32 v16, v24, v16
	v_mul_f32_e32 v17, 0x3fb8aa3b, v17
	v_add_f32_e32 v16, v25, v16
	v_exp_f32_e32 v79, v17
	v_add_f32_e32 v16, v72, v16
	v_add_f32_e32 v16, v74, v16
	v_add_f32_e32 v16, v77, v16
	v_add_f32_e32 v17, v79, v16
	v_sub_f32_e32 v16, v21, v87
	v_mul_f32_e32 v16, 0x3fb8aa3b, v16
	v_exp_f32_e32 v16, v16
	v_sub_f32_e32 v21, 0xff800000, v87
	v_mul_f32_e32 v21, 0x3fb8aa3b, v21
	v_exp_f32_e32 v21, v21
	v_add_f32_e32 v18, v16, v17
	v_sub_f32_e32 v17, v20, v87
	v_mul_f32_e32 v17, 0x3fb8aa3b, v17
	v_exp_f32_e32 v17, v17
	v_sub_f32_e32 v33, v33, v87
	v_mul_f32_e32 v33, 0x3fb8aa3b, v33
	v_exp_f32_e32 v33, v33
	v_add_f32_e32 v19, v17, v18
	v_sub_f32_e32 v18, v106, v87
	v_mul_f32_e32 v18, 0x3fb8aa3b, v18
	v_exp_f32_e32 v18, v18
	s_nop 0
	v_add_f32_e32 v20, v18, v19
	v_sub_f32_e32 v19, v105, v87
	v_mul_f32_e32 v19, 0x3fb8aa3b, v19
	v_exp_f32_e32 v19, v19
	s_nop 0
	v_add_f32_e32 v20, v19, v20
	v_add_f32_e32 v20, v21, v20
	v_add_f32_e32 v20, v21, v20
	v_add_f32_e32 v20, v21, v20
	v_add_f32_e32 v20, v21, v20
	ds_bpermute_b32 v82, v43, v20
	s_waitcnt lgkmcnt(0)
; __device__ __forceinline__ unsigned cvt_pk_bf16(float lo, float hi) { unsigned r; asm volatile("v_cvt_pk_bf16_f32 %0, %1, %2" : "=v"(r) : "v"(lo), "v"(hi)); return r; }
; __device__ __forceinline__ void attn_phase(unsigned char* smem, const Params& P, int layer) {
;     ...
;             const float linv = 1.0f / l;
;             f32x4 o[4];
; #pragma unroll
;             for (int dt = 0; dt < 4; ++dt) o[dt] = (f32x4){0.f, 0.f, 0.f, 0.f};
; #pragma unroll
;             for (int pp = 0; pp < 5; ++pp) { const int tA = w + 2 * pp, tB = tA + 1, cA_ = tA < 15 ? tA : 15, cB_ = tB < 15 ? tB : 15;
;                 u32x4 pw; pw.x = cvt_pk_bf16(sc[2 * pp][0], sc[2 * pp][1]); pw.y = cvt_pk_bf16(sc[2 * pp][2], sc[2 * pp][3]); pw.z = cvt_pk_bf16(sc[2 * pp + 1][0], sc[2 * pp + 1][1]); pw.w = cvt_pk_bf16(sc[2 * pp + 1][2], sc[2 * pp + 1][3]);
;                 bf16x8 Pf; __builtin_memcpy(&Pf, &pw, 16);
; #pragma unroll
;                 for (int dt = 0; dt < 4; ++dt) { const bf16_t* vr = Vl + (16 * dt + ql) * 264 + 4 * q4; const u32x2 va = *(const u32x2*)(vr + 16 * cA_), vb = *(const u32x2*)(vr + 16 * cB_);
;                     u32x4 vw; vw.x = va.x; vw.y = va.y; vw.z = vb.x; vw.w = vb.y; bf16x8 Vf; __builtin_memcpy(&Vf, &vw, 16);
;                     o[dt] = __builtin_amdgcn_mfma_f32_16x16x32_bf16(Pf, Vf, o[dt], 0, 0, 0); } }
; #pragma unroll
;             for (int j = 0; j < 4; ++j) { const float li = __shfl(linv, 4 * q4 + j); bf16_t* op = zb + ((size_t)(b * SEQ + s0 + 16 * w + 4 * q4 + j)) * ZW + 2048 + h * 64 + ql;
; #pragma unroll
;                 for (int dt = 0; dt < 4; ++dt) op[16 * dt] = (bf16_t)(cvt_pk_bf16(o[dt][j] * li, 0.f) & 0xffff); }
	v_add_f32_e32 v20, v20, v82
	ds_bpermute_b32 v82, v44, v20
	s_waitcnt lgkmcnt(0)
	v_add_f32_e32 v20, v20, v82
	ds_read_b64 v[144:145], v62 offset:36864
	ds_read_b64 v[146:147], v63 offset:36896
	ds_read_b64 v[148:149], v62 offset:45312
	ds_read_b64 v[150:151], v63 offset:45344
	ds_read_b64 v[152:153], v62 offset:53760
	ds_read_b64 v[154:155], v63 offset:53792
	ds_read_b64 v[156:157], v62 offset:62208
	ds_read_b64 v[158:159], v63 offset:62240
	ds_read_b64 v[160:161], v64 offset:36864
	ds_read_b64 v[162:163], v65 offset:36896
	ds_read_b64 v[164:165], v64 offset:45312
	ds_read_b64 v[166:167], v65 offset:45344
	ds_read_b64 v[172:173], v64 offset:53760
	ds_read_b64 v[174:175], v65 offset:53792
	ds_read_b64 v[176:177], v64 offset:62208
	ds_read_b64 v[178:179], v65 offset:62240
	v_cvt_pk_bf16_f32 v124, v26, v75
	v_cvt_pk_bf16_f32 v125, v81, v107
	v_cvt_pk_bf16_f32 v126, v108, v109
	v_cvt_pk_bf16_f32 v127, v110, v111
	v_cvt_pk_bf16_f32 v128, v80, v112
	v_cvt_pk_bf16_f32 v129, v113, v114
	v_cvt_pk_bf16_f32 v130, v115, v116
	v_cvt_pk_bf16_f32 v131, v117, v118
	v_cvt_pk_bf16_f32 v132, v27, v73
	v_cvt_pk_bf16_f32 v133, v76, v78
	v_cvt_pk_bf16_f32 v134, v119, v120
	v_cvt_pk_bf16_f32 v135, v121, v122
	v_cvt_pk_bf16_f32 v136, v22, v23
	v_cvt_pk_bf16_f32 v137, v24, v25
	v_cvt_pk_bf16_f32 v138, v72, v74
	v_cvt_pk_bf16_f32 v139, v77, v79
	v_cvt_pk_bf16_f32 v140, v16, v17
	v_cvt_pk_bf16_f32 v141, v18, v19
	v_cvt_pk_bf16_f32 v142, v21, v21
	v_cvt_pk_bf16_f32 v143, v21, v21
	v_add_f32_e32 v20, v33, v20
	s_waitcnt lgkmcnt(8)
	v_mfma_f32_16x16x32_bf16 v[16:19], v[124:127], v[144:147], 0
	v_mfma_f32_16x16x32_bf16 v[72:75], v[124:127], v[148:151], 0
	v_mfma_f32_16x16x32_bf16 v[76:79], v[124:127], v[152:155], 0
	v_mfma_f32_16x16x32_bf16 v[22:25], v[124:127], v[156:159], 0
	ds_read_b64 v[180:181], v66 offset:36864
	ds_read_b64 v[182:183], v67 offset:36896
	ds_read_b64 v[196:197], v66 offset:45312
	ds_read_b64 v[198:199], v67 offset:45344
	ds_read_b64 v[200:201], v66 offset:53760
	ds_read_b64 v[202:203], v67 offset:53792
	ds_read_b64 v[204:205], v66 offset:62208
	ds_read_b64 v[206:207], v67 offset:62240
	s_waitcnt lgkmcnt(8)
	v_mfma_f32_16x16x32_bf16 v[16:19], v[128:131], v[160:163], v[16:19]
	v_mfma_f32_16x16x32_bf16 v[72:75], v[128:131], v[164:167], v[72:75]
	v_mfma_f32_16x16x32_bf16 v[76:79], v[128:131], v[172:175], v[76:79]
	v_mfma_f32_16x16x32_bf16 v[22:25], v[128:131], v[176:179], v[22:25]
	ds_read_b64 v[208:209], v68 offset:36864
	ds_read_b64 v[210:211], v69 offset:36896
	ds_read_b64 v[212:213], v68 offset:45312
	ds_read_b64 v[214:215], v69 offset:45344
	ds_read_b64 v[216:217], v68 offset:53760
	ds_read_b64 v[218:219], v69 offset:53792
	ds_read_b64 v[220:221], v68 offset:62208
	ds_read_b64 v[222:223], v69 offset:62240
	s_waitcnt lgkmcnt(8)
	v_mfma_f32_16x16x32_bf16 v[16:19], v[132:135], v[180:183], v[16:19]
	v_mfma_f32_16x16x32_bf16 v[72:75], v[132:135], v[196:199], v[72:75]
	v_mfma_f32_16x16x32_bf16 v[76:79], v[132:135], v[200:203], v[76:79]
	v_mfma_f32_16x16x32_bf16 v[22:25], v[132:135], v[204:207], v[22:25]
	ds_read_b64 v[224:225], v70 offset:36864
	ds_read_b64 v[226:227], v71 offset:36896
	ds_read_b64 v[234:235], v70 offset:45312
	ds_read_b64 v[236:237], v71 offset:45344
	ds_read_b64 v[238:239], v70 offset:53760
	ds_read_b64 v[240:241], v71 offset:53792
	ds_read_b64 v[242:243], v70 offset:62208
	ds_read_b64 v[244:245], v71 offset:62240
	v_div_scale_f32 v21, s[4:5], v20, v20, 1.0
	v_rcp_f32_e32 v26, v21
	s_mov_b32 s4, 0xae01000
	s_waitcnt lgkmcnt(8)
	v_mfma_f32_16x16x32_bf16 v[16:19], v[136:139], v[208:211], v[16:19]
	v_mfma_f32_16x16x32_bf16 v[72:75], v[136:139], v[212:215], v[72:75]
	v_mfma_f32_16x16x32_bf16 v[76:79], v[136:139], v[216:219], v[76:79]
	v_mfma_f32_16x16x32_bf16 v[22:25], v[136:139], v[220:223], v[22:25]
	v_fma_f32 v27, -v21, v26, 1.0
	v_fmac_f32_e32 v26, v27, v26
	v_div_scale_f32 v27, vcc, 1.0, v20, 1.0
	v_mul_f32_e32 v33, v27, v26
	s_waitcnt lgkmcnt(0)
	v_mfma_f32_16x16x32_bf16 v[16:19], v[140:143], v[224:227], v[16:19]
	v_mfma_f32_16x16x32_bf16 v[72:75], v[140:143], v[234:237], v[72:75]
	v_mfma_f32_16x16x32_bf16 v[76:79], v[140:143], v[238:241], v[76:79]
	v_mfma_f32_16x16x32_bf16 v[22:25], v[140:143], v[242:245], v[22:25]
	v_fma_f32 v80, -v21, v33, v27
	v_fmac_f32_e32 v33, v80, v26
	v_fma_f32 v21, -v21, v33, v27
	v_div_fmas_f32 v21, v21, v26, v33
	v_div_fixup_f32 v33, v21, v20, 1.0
	ds_bpermute_b32 v80, v55, v33
	v_lshl_add_u64 v[20:21], v[38:39], 0, v[34:35]
	v_add_co_u32_e32 v26, vcc, s4, v20
	s_mov_b32 s4, 0xae02000
	s_waitcnt lgkmcnt(0)
	v_mul_f32_e32 v16, v16, v80
	v_cvt_pk_bf16_f32 v16, v16, v1
	v_addc_co_u32_e32 v27, vcc, 0, v21, vcc
	global_store_short v[26:27], v16, off
	v_mul_f32_e32 v16, v72, v80
	v_cvt_pk_bf16_f32 v16, v16, v1
	global_store_short v[26:27], v16, off offset:32
	v_mul_f32_e32 v16, v76, v80
	v_cvt_pk_bf16_f32 v16, v16, v1
	global_store_short v[26:27], v16, off offset:64
	v_mul_f32_e32 v16, v22, v80
	ds_bpermute_b32 v22, v56, v33
	v_cvt_pk_bf16_f32 v16, v16, v1
	global_store_short v[26:27], v16, off offset:96
	v_lshl_add_u64 v[38:39], v[38:39], 0, s[46:47]
	s_waitcnt lgkmcnt(0)
	v_mul_f32_e32 v16, v17, v22
	v_cvt_pk_bf16_f32 v26, v16, v1
	v_add_co_u32_e32 v16, vcc, s4, v20
	s_mov_b32 s4, 0xae03000
	s_nop 0
	v_addc_co_u32_e32 v17, vcc, 0, v21, vcc
	global_store_short v[16:17], v26, off offset:1536
	v_mul_f32_e32 v26, v73, v22
	v_cvt_pk_bf16_f32 v26, v26, v1
	global_store_short v[16:17], v26, off offset:1568
	v_mul_f32_e32 v26, v77, v22
	v_mul_f32_e32 v22, v23, v22
	v_cvt_pk_bf16_f32 v26, v26, v1
	global_store_short v[16:17], v26, off offset:1600
	v_cvt_pk_bf16_f32 v22, v22, v1
	global_store_short v[16:17], v22, off offset:1632
	ds_bpermute_b32 v22, v57, v33
	s_waitcnt lgkmcnt(0)
	v_mul_f32_e32 v16, v18, v22
	v_cvt_pk_bf16_f32 v18, v16, v1
	v_add_co_u32_e32 v16, vcc, s4, v20
	s_mov_b32 s4, 0xae05000
	s_nop 0
	v_addc_co_u32_e32 v17, vcc, 0, v21, vcc
	global_store_short v[16:17], v18, off offset:3072
	v_mul_f32_e32 v18, v74, v22
	v_cvt_pk_bf16_f32 v18, v18, v1
	global_store_short v[16:17], v18, off offset:3104
	v_mul_f32_e32 v18, v78, v22
	v_cvt_pk_bf16_f32 v18, v18, v1
	global_store_short v[16:17], v18, off offset:3136
	v_mul_f32_e32 v18, v24, v22
	v_cvt_pk_bf16_f32 v18, v18, v1
	global_store_short v[16:17], v18, off offset:3168
	ds_bpermute_b32 v18, v58, v33
	s_waitcnt lgkmcnt(0)
	v_mul_f32_e32 v16, v19, v18
	v_cvt_pk_bf16_f32 v19, v16, v1
	v_add_co_u32_e32 v16, vcc, s4, v20
	s_nop 1
	v_addc_co_u32_e32 v17, vcc, 0, v21, vcc
	global_store_short v[16:17], v19, off offset:512
	v_mul_f32_e32 v19, v75, v18
	v_cvt_pk_bf16_f32 v19, v19, v1
	global_store_short v[16:17], v19, off offset:544
	v_mul_f32_e32 v19, v79, v18
	v_mul_f32_e32 v18, v25, v18
	v_cvt_pk_bf16_f32 v19, v19, v1
	global_store_short v[16:17], v19, off offset:576
	v_cvt_pk_bf16_f32 v18, v18, v1
	global_store_short v[16:17], v18, off offset:608
	v_mov_b64_e32 v[22:23], v[14:15]
	v_mov_b64_e32 v[18:19], v[10:11]
	v_mov_b64_e32 v[20:21], v[12:13]
	v_mov_b64_e32 v[16:17], v[8:9]
	s_cbranch_scc1 .LBB0_488
